# P4 v^T epilogue: tile staged in LDS (528-byte rows) and written out as whole 512-byte rows with 16-byte stores instead of 32 row-per-lane 8-byte stores
# speedup vs baseline: 1.0043x; 1.0043x over previous
.LBB0_627:
	s_lshl_b32 s0, s15, 8
	v_mov_b32_e32 v162, v1
	v_mov_b32_e32 v130, v148
	s_or_b32 s0, s0, s67
	s_nop 0
	v_lshl_add_u32 v144, v130, 2, s0
	v_ashrrev_i32_e32 v145, 31, v144
	v_lshl_add_u64 v[130:131], v[144:145], 2, s[40:41]
	global_load_dwordx4 v[130:133], v[130:131], off
	s_lshl_b32 s0, s14, 8
	s_add_i32 s0, s0, s65
	v_and_b32_e32 v153, 63, v162
	v_add_u32_e32 v138, 0xffffc000, v144
	v_add_u32_e32 v159, s0, v162
	v_lshrrev_b32_e32 v138, 9, v138
	v_and_b32_e32 v163, 0xffc, v144
	v_lshlrev_b32_e32 v155, 12, v153
	v_cmp_lt_i32_e32 vcc, s81, v144
	v_and_b32_e32 v158, 0x7ffff8, v138
	v_ashrrev_i32_e32 v154, 6, v159
	v_or3_b32 v138, v163, v155, s82
	s_and_saveexec_b64 s[0:1], vcc
	s_xor_b64 s[0:1], exec, s[0:1]
	v_add_u32_e32 v140, v158, v154
	v_ashrrev_i32_e32 v141, 31, v140
	v_lshlrev_b64 v[140:141], 18, v[140:141]
	v_lshl_add_u64 v[146:147], v[140:141], 0, v[138:139]
	s_or_saveexec_b64 s[0:1], s[0:1]
	v_ashrrev_i32_e32 v140, 10, v144
	v_and_b32_e32 v161, -8, v140
	v_and_b32_e32 v160, 0x1ffc, v144
	s_xor_b64 exec, exec, s[0:1]
	v_add_u32_e32 v140, v161, v154
	v_ashrrev_i32_e32 v141, 31, v140
	v_lshlrev_b64 v[146:147], 19, v[140:141]
	v_lshl_or_b32 v140, v153, 13, v146
	v_or_b32_e32 v146, v140, v160
	s_or_b64 exec, exec, s[0:1]
	v_add_u32_e32 v140, 16, v162
	v_and_b32_e32 v145, 63, v140
	v_mov_b64_e32 v[140:141], s[64:65]
	s_waitcnt vmcnt(0)
	v_pk_fma_f32 v[130:131], v[130:131], s[62:63], v[140:141] op_sel_hi:[1,0,0]
	v_pk_fma_f32 v[132:133], v[132:133], s[62:63], v[140:141] op_sel_hi:[1,0,0]
	v_mul_f32_e32 v142, 0x4b800000, v130
	v_cmp_gt_f32_e64 s[0:1], s82, v130
	v_cmp_gt_f32_e64 s[8:9], s82, v131
	v_mul_f32_e32 v140, 0x4b800000, v132
	v_cndmask_b32_e64 v130, v130, v142, s[0:1]
	v_mul_f32_e32 v142, 0x4b800000, v131
	v_cmp_gt_f32_e64 s[10:11], s82, v132
	v_cndmask_b32_e64 v131, v131, v142, s[8:9]
	v_cmp_gt_f32_e64 s[14:15], s82, v133
	v_cndmask_b32_e64 v132, v132, v140, s[10:11]
	v_mul_f32_e32 v140, 0x4b800000, v133
	v_rsq_f32_e32 v130, v130
	v_rsq_f32_e32 v131, v131
	v_cndmask_b32_e64 v133, v133, v140, s[14:15]
	v_rsq_f32_e32 v132, v132
	v_rsq_f32_e32 v133, v133
	v_pk_mul_f32 v[140:141], v[130:131], s[66:67] op_sel_hi:[1,0]
	v_lshlrev_b32_e32 v156, 12, v145
	v_cndmask_b32_e64 v131, v131, v141, s[8:9]
	v_cndmask_b32_e64 v130, v130, v140, s[0:1]
	v_pk_mul_f32 v[140:141], v[132:133], s[66:67] op_sel_hi:[1,0]
	v_pk_mul_f32 v[126:127], v[126:127], v[130:131]
	v_cndmask_b32_e64 v133, v133, v141, s[14:15]
	v_cndmask_b32_e64 v132, v132, v140, s[10:11]
	v_pk_mul_f32 v[128:129], v[128:129], v[132:133]
	s_waitcnt vmcnt(0)
	s_barrier
	v_readfirstlane_b32 s99, v146
	s_cmp_ge_u32 s99, 0x800000
	s_cselect_b32 s98, 12, 13
	s_add_i32 s100, s98, 8
	s_lshr_b32 s101, s99, s100
	s_lshl_b32 s101, s101, s100
	s_lshl_b32 s100, 1, s98
	s_sub_u32 s100, s100, 0x100
	s_and_b32 s100, s99, s100
	s_or_b32 s101, s101, s100
	s_movk_i32 s100, 0x210
	v_lshrrev_b32_e32 v141, s98, v146
	v_and_b32_e32 v140, 0xff, v146
	v_and_b32_e32 v141, 0xff, v141
	v_lshlrev_b32_e32 v140, 1, v140
	v_mad_u32_u24 v140, v141, s100, v140
	v_cvt_pk_bf16_f32 v126, v126, v127
	v_cvt_pk_bf16_f32 v127, v128, v129
	ds_write_b64 v140, v[126:127]
	v_add_u32_e32 v126, 16, v159
	v_ashrrev_i32_e32 v147, 6, v126
	v_or3_b32 v126, v163, v156, s82
	s_and_saveexec_b64 s[0:1], vcc
	s_xor_b64 s[0:1], exec, s[0:1]
	v_add_u32_e32 v128, v158, v147
	v_ashrrev_i32_e32 v129, 31, v128
	v_lshlrev_b64 v[128:129], 18, v[128:129]
	v_mov_b32_e32 v127, v139
	v_lshl_add_u64 v[128:129], v[128:129], 0, v[126:127]
	s_andn2_saveexec_b64 s[0:1], s[0:1]
	v_add_u32_e32 v128, v161, v147
	v_ashrrev_i32_e32 v129, 31, v128
	v_lshlrev_b64 v[128:129], 19, v[128:129]
	v_lshl_or_b32 v127, v145, 13, v128
	v_or_b32_e32 v128, v127, v160
	s_or_b64 exec, exec, s[0:1]
	v_pk_mul_f32 v[124:125], v[124:125], v[132:133]
	v_pk_mul_f32 v[122:123], v[122:123], v[130:131]
	v_xor_b32_e32 v146, 32, v153
	v_lshrrev_b32_e32 v129, s98, v128
	v_and_b32_e32 v128, 0xff, v128
	v_and_b32_e32 v129, 0xff, v129
	v_lshlrev_b32_e32 v128, 1, v128
	v_mad_u32_u24 v128, v129, s100, v128
	v_cvt_pk_bf16_f32 v122, v122, v123
	v_cvt_pk_bf16_f32 v123, v124, v125
	ds_write_b64 v128, v[122:123]
	v_add_u32_e32 v122, 32, v159
	v_lshlrev_b32_e32 v157, 12, v146
	v_ashrrev_i32_e32 v129, 6, v122
	v_or3_b32 v122, v163, v157, s82
	s_and_saveexec_b64 s[0:1], vcc
	s_xor_b64 s[0:1], exec, s[0:1]
	v_add_u32_e32 v124, v158, v129
	v_ashrrev_i32_e32 v125, 31, v124
	v_lshlrev_b64 v[124:125], 18, v[124:125]
	v_mov_b32_e32 v123, v139
	v_lshl_add_u64 v[124:125], v[124:125], 0, v[122:123]
	s_andn2_saveexec_b64 s[0:1], s[0:1]
	v_add_u32_e32 v124, v161, v129
	v_ashrrev_i32_e32 v125, 31, v124
	v_lshlrev_b64 v[124:125], 19, v[124:125]
	v_lshl_or_b32 v123, v146, 13, v124
	v_or_b32_e32 v124, v123, v160
	s_or_b64 exec, exec, s[0:1]
	v_add_u32_e32 v123, 48, v162
	v_pk_mul_f32 v[120:121], v[120:121], v[132:133]
	v_pk_mul_f32 v[118:119], v[118:119], v[130:131]
	v_and_b32_e32 v128, 63, v123
	v_lshrrev_b32_e32 v125, s98, v124
	v_and_b32_e32 v124, 0xff, v124
	v_and_b32_e32 v125, 0xff, v125
	v_lshlrev_b32_e32 v124, 1, v124
	v_mad_u32_u24 v124, v125, s100, v124
	v_cvt_pk_bf16_f32 v118, v118, v119
	v_cvt_pk_bf16_f32 v119, v120, v121
	ds_write_b64 v124, v[118:119]
	v_add_u32_e32 v118, 48, v159
	v_lshlrev_b32_e32 v125, 12, v128
	v_ashrrev_i32_e32 v124, 6, v118
	v_or3_b32 v118, v163, v125, s82
	s_and_saveexec_b64 s[0:1], vcc
	s_xor_b64 s[0:1], exec, s[0:1]
	v_add_u32_e32 v120, v158, v124
	v_ashrrev_i32_e32 v121, 31, v120
	v_lshlrev_b64 v[120:121], 18, v[120:121]
	v_mov_b32_e32 v119, v139
	v_lshl_add_u64 v[120:121], v[120:121], 0, v[118:119]
	s_andn2_saveexec_b64 s[0:1], s[0:1]
	v_add_u32_e32 v120, v161, v124
	v_ashrrev_i32_e32 v121, 31, v120
	v_lshlrev_b64 v[120:121], 19, v[120:121]
	v_lshl_or_b32 v119, v128, 13, v120
	v_or_b32_e32 v120, v119, v160
	s_or_b64 exec, exec, s[0:1]
	v_pk_mul_f32 v[112:113], v[112:113], v[132:133]
	v_pk_mul_f32 v[110:111], v[110:111], v[130:131]
	v_lshrrev_b32_e32 v121, s98, v120
	v_and_b32_e32 v120, 0xff, v120
	v_and_b32_e32 v121, 0xff, v121
	v_lshlrev_b32_e32 v120, 1, v120
	v_mad_u32_u24 v120, v121, s100, v120
	v_cvt_pk_bf16_f32 v110, v110, v111
	v_cvt_pk_bf16_f32 v111, v112, v113
	ds_write_b64 v120, v[110:111]
	v_add_u32_e32 v110, 0x80, v159
	v_ashrrev_i32_e32 v113, 6, v110
	s_and_saveexec_b64 s[0:1], vcc
	s_xor_b64 s[0:1], exec, s[0:1]
	v_add_u32_e32 v110, v158, v113
	v_ashrrev_i32_e32 v111, 31, v110
	v_lshlrev_b64 v[110:111], 18, v[110:111]
	v_lshl_add_u64 v[110:111], v[110:111], 0, v[138:139]
	s_andn2_saveexec_b64 s[0:1], s[0:1]
	v_add_u32_e32 v110, v161, v113
	v_ashrrev_i32_e32 v111, 31, v110
	v_lshlrev_b64 v[110:111], 19, v[110:111]
	v_lshl_or_b32 v110, v153, 13, v110
	v_or_b32_e32 v110, v110, v160
	s_or_b64 exec, exec, s[0:1]
	v_pk_mul_f32 v[116:117], v[116:117], v[132:133]
	v_pk_mul_f32 v[114:115], v[114:115], v[130:131]
	v_lshrrev_b32_e32 v111, s98, v110
	v_and_b32_e32 v110, 0xff, v110
	v_and_b32_e32 v111, 0xff, v111
	v_lshlrev_b32_e32 v110, 1, v110
	v_mad_u32_u24 v110, v111, s100, v110
	v_cvt_pk_bf16_f32 v114, v114, v115
	v_cvt_pk_bf16_f32 v115, v116, v117
	ds_write_b64 v110, v[114:115]
	v_add_u32_e32 v110, 0x90, v159
	v_ashrrev_i32_e32 v112, 6, v110
	s_and_saveexec_b64 s[0:1], vcc
	s_xor_b64 s[0:1], exec, s[0:1]
	v_add_u32_e32 v110, v158, v112
	v_ashrrev_i32_e32 v111, 31, v110
	v_lshlrev_b64 v[110:111], 18, v[110:111]
	v_mov_b32_e32 v127, v139
	v_lshl_add_u64 v[110:111], v[110:111], 0, v[126:127]
	s_andn2_saveexec_b64 s[0:1], s[0:1]
	v_add_u32_e32 v110, v161, v112
	v_ashrrev_i32_e32 v111, 31, v110
	v_lshlrev_b64 v[110:111], 19, v[110:111]
	v_lshl_or_b32 v110, v145, 13, v110
	v_or_b32_e32 v110, v110, v160
	s_or_b64 exec, exec, s[0:1]
	v_pk_mul_f32 v[108:109], v[108:109], v[132:133]
	v_pk_mul_f32 v[106:107], v[106:107], v[130:131]
	v_lshrrev_b32_e32 v111, s98, v110
	v_and_b32_e32 v110, 0xff, v110
	v_and_b32_e32 v111, 0xff, v111
	v_lshlrev_b32_e32 v110, 1, v110
	v_mad_u32_u24 v110, v111, s100, v110
	v_cvt_pk_bf16_f32 v106, v106, v107
	v_cvt_pk_bf16_f32 v107, v108, v109
	ds_write_b64 v110, v[106:107]
	v_add_u32_e32 v106, 0xa0, v159
	v_ashrrev_i32_e32 v108, 6, v106
	s_and_saveexec_b64 s[0:1], vcc
	s_xor_b64 s[0:1], exec, s[0:1]
	v_add_u32_e32 v106, v158, v108
	v_ashrrev_i32_e32 v107, 31, v106
	v_lshlrev_b64 v[106:107], 18, v[106:107]
	v_mov_b32_e32 v123, v139
	v_lshl_add_u64 v[106:107], v[106:107], 0, v[122:123]
	s_andn2_saveexec_b64 s[0:1], s[0:1]
	v_add_u32_e32 v106, v161, v108
	v_ashrrev_i32_e32 v107, 31, v106
	v_lshlrev_b64 v[106:107], 19, v[106:107]
	v_lshl_or_b32 v106, v146, 13, v106
	v_or_b32_e32 v106, v106, v160
	s_or_b64 exec, exec, s[0:1]
	v_pk_mul_f32 v[104:105], v[104:105], v[132:133]
	v_pk_mul_f32 v[102:103], v[102:103], v[130:131]
	v_lshrrev_b32_e32 v107, s98, v106
	v_and_b32_e32 v106, 0xff, v106
	v_and_b32_e32 v107, 0xff, v107
	v_lshlrev_b32_e32 v106, 1, v106
	v_mad_u32_u24 v106, v107, s100, v106
	v_cvt_pk_bf16_f32 v102, v102, v103
	v_cvt_pk_bf16_f32 v103, v104, v105
	ds_write_b64 v106, v[102:103]
	v_add_u32_e32 v102, 0xb0, v159
	v_ashrrev_i32_e32 v106, 6, v102
	s_and_saveexec_b64 s[0:1], vcc
	s_xor_b64 s[0:1], exec, s[0:1]
	v_add_u32_e32 v102, v158, v106
	v_ashrrev_i32_e32 v103, 31, v102
	v_lshlrev_b64 v[102:103], 18, v[102:103]
	v_mov_b32_e32 v119, v139
	v_lshl_add_u64 v[102:103], v[102:103], 0, v[118:119]
	s_andn2_saveexec_b64 s[0:1], s[0:1]
	v_add_u32_e32 v102, v161, v106
	v_ashrrev_i32_e32 v103, 31, v102
	v_lshlrev_b64 v[102:103], 19, v[102:103]
	v_lshl_or_b32 v102, v128, 13, v102
	v_or_b32_e32 v102, v102, v160
	s_or_b64 exec, exec, s[0:1]
	v_pk_mul_f32 v[100:101], v[100:101], v[132:133]
	v_pk_mul_f32 v[98:99], v[98:99], v[130:131]
	v_add_u32_e32 v104, 16, v144
	v_lshrrev_b32_e32 v103, s98, v102
	v_and_b32_e32 v102, 0xff, v102
	v_and_b32_e32 v103, 0xff, v103
	v_lshlrev_b32_e32 v102, 1, v102
	v_mad_u32_u24 v102, v103, s100, v102
	v_cvt_pk_bf16_f32 v98, v98, v99
	v_cvt_pk_bf16_f32 v99, v100, v101
	v_ashrrev_i32_e32 v105, 31, v104
	ds_write_b64 v102, v[98:99]
	v_lshl_add_u64 v[98:99], v[104:105], 2, s[40:41]
	global_load_dwordx4 v[98:101], v[98:99], off
	v_add_u32_e32 v102, 0xffffc010, v144
	v_lshrrev_b32_e32 v102, 9, v102
	v_and_b32_e32 v109, 0xffc, v104
	v_cmp_lt_i32_e32 vcc, s81, v104
	v_and_b32_e32 v105, 0x7ffff8, v102
	v_or3_b32 v138, v109, v155, s82
	s_and_saveexec_b64 s[0:1], vcc
	s_xor_b64 s[0:1], exec, s[0:1]
	v_add_u32_e32 v102, v105, v154
	v_ashrrev_i32_e32 v103, 31, v102
	v_lshlrev_b64 v[102:103], 18, v[102:103]
	v_lshl_add_u64 v[102:103], v[102:103], 0, v[138:139]
	s_or_saveexec_b64 s[0:1], s[0:1]
	v_ashrrev_i32_e32 v107, 10, v104
	v_and_b32_e32 v107, -8, v107
	v_and_b32_e32 v104, 0x1ffc, v104
	s_xor_b64 exec, exec, s[0:1]
	v_add_u32_e32 v102, v107, v154
	v_ashrrev_i32_e32 v103, 31, v102
	v_lshlrev_b64 v[102:103], 19, v[102:103]
	v_lshl_or_b32 v102, v153, 13, v102
	v_or_b32_e32 v102, v102, v104
	s_or_b64 exec, exec, s[0:1]
	v_mov_b64_e32 v[110:111], s[64:65]
	s_waitcnt vmcnt(0)
	v_pk_fma_f32 v[98:99], v[98:99], s[62:63], v[110:111] op_sel_hi:[1,0,0]
	v_pk_fma_f32 v[100:101], v[100:101], s[62:63], v[110:111] op_sel_hi:[1,0,0]
	v_mul_f32_e32 v114, 0x4b800000, v98
	v_cmp_gt_f32_e64 s[0:1], s82, v98
	v_cmp_gt_f32_e64 s[8:9], s82, v99
	v_mul_f32_e32 v110, 0x4b800000, v100
	v_cndmask_b32_e64 v98, v98, v114, s[0:1]
	v_mul_f32_e32 v114, 0x4b800000, v99
	v_cmp_gt_f32_e64 s[10:11], s82, v100
	v_cndmask_b32_e64 v99, v99, v114, s[8:9]
	v_cmp_gt_f32_e64 s[14:15], s82, v101
	v_cndmask_b32_e64 v100, v100, v110, s[10:11]
	v_mul_f32_e32 v110, 0x4b800000, v101
	v_rsq_f32_e32 v98, v98
	v_rsq_f32_e32 v99, v99
	v_cndmask_b32_e64 v101, v101, v110, s[14:15]
	v_rsq_f32_e32 v100, v100
	v_rsq_f32_e32 v101, v101
	v_pk_mul_f32 v[110:111], v[98:99], s[66:67] op_sel_hi:[1,0]
	v_lshrrev_b32_e32 v103, s98, v102
	v_and_b32_e32 v102, 0xff, v102
	v_and_b32_e32 v103, 0xff, v103
	v_lshlrev_b32_e32 v102, 1, v102
	v_mad_u32_u24 v102, v103, s100, v102
	v_cndmask_b32_e64 v99, v99, v111, s[8:9]
	v_cndmask_b32_e64 v98, v98, v110, s[0:1]
	v_pk_mul_f32 v[110:111], v[100:101], s[66:67] op_sel_hi:[1,0]
	v_pk_mul_f32 v[94:95], v[94:95], v[98:99]
	v_cndmask_b32_e64 v101, v101, v111, s[14:15]
	v_cndmask_b32_e64 v100, v100, v110, s[10:11]
	v_pk_mul_f32 v[96:97], v[96:97], v[100:101]
	v_cvt_pk_bf16_f32 v94, v94, v95
	v_cvt_pk_bf16_f32 v95, v96, v97
	ds_write_b64 v102, v[94:95]
	v_or3_b32 v94, v109, v156, s82
	s_and_saveexec_b64 s[0:1], vcc
	s_xor_b64 s[0:1], exec, s[0:1]
	v_add_u32_e32 v96, v105, v147
	v_ashrrev_i32_e32 v97, 31, v96
	v_lshlrev_b64 v[96:97], 18, v[96:97]
	v_mov_b32_e32 v95, v139
	v_lshl_add_u64 v[96:97], v[96:97], 0, v[94:95]
	s_andn2_saveexec_b64 s[0:1], s[0:1]
	v_add_u32_e32 v96, v107, v147
	v_ashrrev_i32_e32 v97, 31, v96
	v_lshlrev_b64 v[96:97], 19, v[96:97]
	v_lshl_or_b32 v95, v145, 13, v96
	v_or_b32_e32 v96, v95, v104
	s_or_b64 exec, exec, s[0:1]
	v_pk_mul_f32 v[92:93], v[92:93], v[100:101]
	v_pk_mul_f32 v[90:91], v[90:91], v[98:99]
	v_lshrrev_b32_e32 v97, s98, v96
	v_and_b32_e32 v96, 0xff, v96
	v_and_b32_e32 v97, 0xff, v97
	v_lshlrev_b32_e32 v96, 1, v96
	v_mad_u32_u24 v96, v97, s100, v96
	v_cvt_pk_bf16_f32 v90, v90, v91
	v_cvt_pk_bf16_f32 v91, v92, v93
	ds_write_b64 v96, v[90:91]
	v_or3_b32 v90, v109, v157, s82
	s_and_saveexec_b64 s[0:1], vcc
	s_xor_b64 s[0:1], exec, s[0:1]
	v_add_u32_e32 v92, v105, v129
	v_ashrrev_i32_e32 v93, 31, v92
	v_lshlrev_b64 v[92:93], 18, v[92:93]
	v_mov_b32_e32 v91, v139
	v_lshl_add_u64 v[92:93], v[92:93], 0, v[90:91]
	s_andn2_saveexec_b64 s[0:1], s[0:1]
	v_add_u32_e32 v92, v107, v129
	v_ashrrev_i32_e32 v93, 31, v92
	v_lshlrev_b64 v[92:93], 19, v[92:93]
	v_lshl_or_b32 v91, v146, 13, v92
	v_or_b32_e32 v92, v91, v104
	s_or_b64 exec, exec, s[0:1]
	v_pk_mul_f32 v[88:89], v[88:89], v[100:101]
	v_pk_mul_f32 v[86:87], v[86:87], v[98:99]
	v_lshrrev_b32_e32 v93, s98, v92
	v_and_b32_e32 v92, 0xff, v92
	v_and_b32_e32 v93, 0xff, v93
	v_lshlrev_b32_e32 v92, 1, v92
	v_mad_u32_u24 v92, v93, s100, v92
	v_cvt_pk_bf16_f32 v86, v86, v87
	v_cvt_pk_bf16_f32 v87, v88, v89
	ds_write_b64 v92, v[86:87]
	v_or3_b32 v86, v109, v125, s82
	s_and_saveexec_b64 s[0:1], vcc
	s_xor_b64 s[0:1], exec, s[0:1]
	v_add_u32_e32 v88, v105, v124
	v_ashrrev_i32_e32 v89, 31, v88
	v_lshlrev_b64 v[88:89], 18, v[88:89]
	v_mov_b32_e32 v87, v139
	v_lshl_add_u64 v[88:89], v[88:89], 0, v[86:87]
	s_andn2_saveexec_b64 s[0:1], s[0:1]
	v_add_u32_e32 v88, v107, v124
	v_ashrrev_i32_e32 v89, 31, v88
	v_lshlrev_b64 v[88:89], 19, v[88:89]
	v_lshl_or_b32 v87, v128, 13, v88
	v_or_b32_e32 v88, v87, v104
	s_or_b64 exec, exec, s[0:1]
	v_pk_mul_f32 v[80:81], v[80:81], v[100:101]
	v_pk_mul_f32 v[78:79], v[78:79], v[98:99]
	v_lshrrev_b32_e32 v89, s98, v88
	v_and_b32_e32 v88, 0xff, v88
	v_and_b32_e32 v89, 0xff, v89
	v_lshlrev_b32_e32 v88, 1, v88
	v_mad_u32_u24 v88, v89, s100, v88
	v_cvt_pk_bf16_f32 v78, v78, v79
	v_cvt_pk_bf16_f32 v79, v80, v81
	ds_write_b64 v88, v[78:79]
	s_and_saveexec_b64 s[0:1], vcc
	s_xor_b64 s[0:1], exec, s[0:1]
	v_add_u32_e32 v78, v105, v113
	v_ashrrev_i32_e32 v79, 31, v78
	v_lshlrev_b64 v[78:79], 18, v[78:79]
	v_lshl_add_u64 v[78:79], v[78:79], 0, v[138:139]
	s_andn2_saveexec_b64 s[0:1], s[0:1]
	v_add_u32_e32 v78, v107, v113
	v_ashrrev_i32_e32 v79, 31, v78
	v_lshlrev_b64 v[78:79], 19, v[78:79]
	v_lshl_or_b32 v78, v153, 13, v78
	v_or_b32_e32 v78, v78, v104
	s_or_b64 exec, exec, s[0:1]
	v_pk_mul_f32 v[80:81], v[84:85], v[100:101]
	v_pk_mul_f32 v[82:83], v[82:83], v[98:99]
	v_lshrrev_b32_e32 v79, s98, v78
	v_and_b32_e32 v78, 0xff, v78
	v_and_b32_e32 v79, 0xff, v79
	v_lshlrev_b32_e32 v78, 1, v78
	v_mad_u32_u24 v78, v79, s100, v78
	v_cvt_pk_bf16_f32 v82, v82, v83
	v_cvt_pk_bf16_f32 v83, v80, v81
	ds_write_b64 v78, v[82:83]
	s_and_saveexec_b64 s[0:1], vcc
	s_xor_b64 s[0:1], exec, s[0:1]
	v_add_u32_e32 v78, v105, v112
	v_ashrrev_i32_e32 v79, 31, v78
	v_lshlrev_b64 v[78:79], 18, v[78:79]
	v_mov_b32_e32 v95, v139
	v_lshl_add_u64 v[78:79], v[78:79], 0, v[94:95]
	s_andn2_saveexec_b64 s[0:1], s[0:1]
	v_add_u32_e32 v78, v107, v112
	v_ashrrev_i32_e32 v79, 31, v78
	v_lshlrev_b64 v[78:79], 19, v[78:79]
	v_lshl_or_b32 v78, v145, 13, v78
	v_or_b32_e32 v78, v78, v104
	s_or_b64 exec, exec, s[0:1]
	v_pk_mul_f32 v[76:77], v[76:77], v[100:101]
	v_pk_mul_f32 v[74:75], v[74:75], v[98:99]
	v_lshrrev_b32_e32 v79, s98, v78
	v_and_b32_e32 v78, 0xff, v78
	v_and_b32_e32 v79, 0xff, v79
	v_lshlrev_b32_e32 v78, 1, v78
	v_mad_u32_u24 v78, v79, s100, v78
	v_cvt_pk_bf16_f32 v74, v74, v75
	v_cvt_pk_bf16_f32 v75, v76, v77
	ds_write_b64 v78, v[74:75]
	s_and_saveexec_b64 s[0:1], vcc
	s_xor_b64 s[0:1], exec, s[0:1]
	v_add_u32_e32 v74, v105, v108
	v_ashrrev_i32_e32 v75, 31, v74
	v_lshlrev_b64 v[74:75], 18, v[74:75]
	v_mov_b32_e32 v91, v139
	v_lshl_add_u64 v[74:75], v[74:75], 0, v[90:91]
	s_andn2_saveexec_b64 s[0:1], s[0:1]
	v_add_u32_e32 v74, v107, v108
	v_ashrrev_i32_e32 v75, 31, v74
	v_lshlrev_b64 v[74:75], 19, v[74:75]
	v_lshl_or_b32 v74, v146, 13, v74
	v_or_b32_e32 v74, v74, v104
	s_or_b64 exec, exec, s[0:1]
	v_pk_mul_f32 v[72:73], v[72:73], v[100:101]
	v_pk_mul_f32 v[70:71], v[70:71], v[98:99]
	v_lshrrev_b32_e32 v75, s98, v74
	v_and_b32_e32 v74, 0xff, v74
	v_and_b32_e32 v75, 0xff, v75
	v_lshlrev_b32_e32 v74, 1, v74
	v_mad_u32_u24 v74, v75, s100, v74
	v_cvt_pk_bf16_f32 v70, v70, v71
	v_cvt_pk_bf16_f32 v71, v72, v73
	ds_write_b64 v74, v[70:71]
	s_and_saveexec_b64 s[0:1], vcc
	s_xor_b64 s[0:1], exec, s[0:1]
	v_add_u32_e32 v70, v105, v106
	v_ashrrev_i32_e32 v71, 31, v70
	v_lshlrev_b64 v[70:71], 18, v[70:71]
	v_mov_b32_e32 v87, v139
	v_lshl_add_u64 v[70:71], v[70:71], 0, v[86:87]
	s_andn2_saveexec_b64 s[0:1], s[0:1]
	v_add_u32_e32 v70, v107, v106
	v_ashrrev_i32_e32 v71, 31, v70
	v_lshlrev_b64 v[70:71], 19, v[70:71]
	v_lshl_or_b32 v70, v128, 13, v70
	v_or_b32_e32 v70, v70, v104
	s_or_b64 exec, exec, s[0:1]
	v_pk_mul_f32 v[68:69], v[68:69], v[100:101]
	v_pk_mul_f32 v[66:67], v[66:67], v[98:99]
	v_add_u32_e32 v72, 0x80, v144
	v_lshrrev_b32_e32 v71, s98, v70
	v_and_b32_e32 v70, 0xff, v70
	v_and_b32_e32 v71, 0xff, v71
	v_lshlrev_b32_e32 v70, 1, v70
	v_mad_u32_u24 v70, v71, s100, v70
	v_cvt_pk_bf16_f32 v66, v66, v67
	v_cvt_pk_bf16_f32 v67, v68, v69
	v_ashrrev_i32_e32 v73, 31, v72
	ds_write_b64 v70, v[66:67]
	v_lshl_add_u64 v[66:67], v[72:73], 2, s[40:41]
	global_load_dwordx4 v[66:69], v[66:67], off
	v_add_u32_e32 v70, 0xffffc080, v144
	v_lshrrev_b32_e32 v70, 9, v70
	v_and_b32_e32 v75, 0xffc, v72
	v_cmp_lt_i32_e32 vcc, s81, v72
	v_and_b32_e32 v73, 0x7ffff8, v70
	v_or3_b32 v138, v75, v155, s82
	s_and_saveexec_b64 s[0:1], vcc
	s_xor_b64 s[0:1], exec, s[0:1]
	v_add_u32_e32 v70, v73, v154
	v_ashrrev_i32_e32 v71, 31, v70
	v_lshlrev_b64 v[70:71], 18, v[70:71]
	v_lshl_add_u64 v[70:71], v[70:71], 0, v[138:139]
	s_or_saveexec_b64 s[0:1], s[0:1]
	v_ashrrev_i32_e32 v74, 10, v72
	v_and_b32_e32 v74, -8, v74
	v_and_b32_e32 v72, 0x1ffc, v72
	s_xor_b64 exec, exec, s[0:1]
	v_add_u32_e32 v70, v74, v154
	v_ashrrev_i32_e32 v71, 31, v70
	v_lshlrev_b64 v[70:71], 19, v[70:71]
	v_lshl_or_b32 v70, v153, 13, v70
	v_or_b32_e32 v70, v70, v72
	s_or_b64 exec, exec, s[0:1]
	v_mov_b64_e32 v[76:77], s[64:65]
	s_waitcnt vmcnt(0)
	v_pk_fma_f32 v[66:67], v[66:67], s[62:63], v[76:77] op_sel_hi:[1,0,0]
	v_pk_fma_f32 v[68:69], v[68:69], s[62:63], v[76:77] op_sel_hi:[1,0,0]
	v_mul_f32_e32 v78, 0x4b800000, v66
	v_cmp_gt_f32_e64 s[0:1], s82, v66
	v_cmp_gt_f32_e64 s[8:9], s82, v67
	v_mul_f32_e32 v76, 0x4b800000, v68
	v_cndmask_b32_e64 v66, v66, v78, s[0:1]
	v_mul_f32_e32 v78, 0x4b800000, v67
	v_cmp_gt_f32_e64 s[10:11], s82, v68
	v_cndmask_b32_e64 v67, v67, v78, s[8:9]
	v_cmp_gt_f32_e64 s[14:15], s82, v69
	v_cndmask_b32_e64 v68, v68, v76, s[10:11]
	v_mul_f32_e32 v76, 0x4b800000, v69
	v_rsq_f32_e32 v66, v66
	v_rsq_f32_e32 v67, v67
	v_cndmask_b32_e64 v69, v69, v76, s[14:15]
	v_rsq_f32_e32 v68, v68
	v_rsq_f32_e32 v69, v69
	v_pk_mul_f32 v[76:77], v[66:67], s[66:67] op_sel_hi:[1,0]
	v_lshrrev_b32_e32 v71, s98, v70
	v_and_b32_e32 v70, 0xff, v70
	v_and_b32_e32 v71, 0xff, v71
	v_lshlrev_b32_e32 v70, 1, v70
	v_mad_u32_u24 v70, v71, s100, v70
	v_cndmask_b32_e64 v67, v67, v77, s[8:9]
	v_cndmask_b32_e64 v66, v66, v76, s[0:1]
	v_pk_mul_f32 v[76:77], v[68:69], s[66:67] op_sel_hi:[1,0]
	v_pk_mul_f32 v[62:63], v[62:63], v[66:67]
	v_cndmask_b32_e64 v69, v69, v77, s[14:15]
	v_cndmask_b32_e64 v68, v68, v76, s[10:11]
	v_pk_mul_f32 v[64:65], v[64:65], v[68:69]
	v_cvt_pk_bf16_f32 v62, v62, v63
	v_cvt_pk_bf16_f32 v63, v64, v65
	ds_write_b64 v70, v[62:63]
	v_or3_b32 v62, v75, v156, s82
	s_and_saveexec_b64 s[0:1], vcc
	s_xor_b64 s[0:1], exec, s[0:1]
	v_add_u32_e32 v64, v73, v147
	v_ashrrev_i32_e32 v65, 31, v64
	v_lshlrev_b64 v[64:65], 18, v[64:65]
	v_mov_b32_e32 v63, v139
	v_lshl_add_u64 v[64:65], v[64:65], 0, v[62:63]
	s_andn2_saveexec_b64 s[0:1], s[0:1]
	v_add_u32_e32 v64, v74, v147
	v_ashrrev_i32_e32 v65, 31, v64
	v_lshlrev_b64 v[64:65], 19, v[64:65]
	v_lshl_or_b32 v63, v145, 13, v64
	v_or_b32_e32 v64, v63, v72
	s_or_b64 exec, exec, s[0:1]
	v_pk_mul_f32 v[60:61], v[60:61], v[68:69]
	v_pk_mul_f32 v[58:59], v[58:59], v[66:67]
	v_lshrrev_b32_e32 v65, s98, v64
	v_and_b32_e32 v64, 0xff, v64
	v_and_b32_e32 v65, 0xff, v65
	v_lshlrev_b32_e32 v64, 1, v64
	v_mad_u32_u24 v64, v65, s100, v64
	v_cvt_pk_bf16_f32 v58, v58, v59
	v_cvt_pk_bf16_f32 v59, v60, v61
	ds_write_b64 v64, v[58:59]
	v_or3_b32 v58, v75, v157, s82
	s_and_saveexec_b64 s[0:1], vcc
	s_xor_b64 s[0:1], exec, s[0:1]
	v_add_u32_e32 v60, v73, v129
	v_ashrrev_i32_e32 v61, 31, v60
	v_lshlrev_b64 v[60:61], 18, v[60:61]
	v_mov_b32_e32 v59, v139
	v_lshl_add_u64 v[60:61], v[60:61], 0, v[58:59]
	s_andn2_saveexec_b64 s[0:1], s[0:1]
	v_add_u32_e32 v60, v74, v129
	v_ashrrev_i32_e32 v61, 31, v60
	v_lshlrev_b64 v[60:61], 19, v[60:61]
	v_lshl_or_b32 v59, v146, 13, v60
	v_or_b32_e32 v60, v59, v72
	s_or_b64 exec, exec, s[0:1]
	v_pk_mul_f32 v[56:57], v[56:57], v[68:69]
	v_pk_mul_f32 v[54:55], v[54:55], v[66:67]
	v_lshrrev_b32_e32 v61, s98, v60
	v_and_b32_e32 v60, 0xff, v60
	v_and_b32_e32 v61, 0xff, v61
	v_lshlrev_b32_e32 v60, 1, v60
	v_mad_u32_u24 v60, v61, s100, v60
	v_cvt_pk_bf16_f32 v54, v54, v55
	v_cvt_pk_bf16_f32 v55, v56, v57
	ds_write_b64 v60, v[54:55]
	v_or3_b32 v54, v75, v125, s82
	s_and_saveexec_b64 s[0:1], vcc
	s_xor_b64 s[0:1], exec, s[0:1]
	v_add_u32_e32 v56, v73, v124
	v_ashrrev_i32_e32 v57, 31, v56
	v_lshlrev_b64 v[56:57], 18, v[56:57]
	v_mov_b32_e32 v55, v139
	v_lshl_add_u64 v[56:57], v[56:57], 0, v[54:55]
	s_andn2_saveexec_b64 s[0:1], s[0:1]
	v_add_u32_e32 v56, v74, v124
	v_ashrrev_i32_e32 v57, 31, v56
	v_lshlrev_b64 v[56:57], 19, v[56:57]
	v_lshl_or_b32 v55, v128, 13, v56
	v_or_b32_e32 v56, v55, v72
	s_or_b64 exec, exec, s[0:1]
	v_pk_mul_f32 v[48:49], v[48:49], v[68:69]
	v_pk_mul_f32 v[46:47], v[46:47], v[66:67]
	v_lshrrev_b32_e32 v57, s98, v56
	v_and_b32_e32 v56, 0xff, v56
	v_and_b32_e32 v57, 0xff, v57
	v_lshlrev_b32_e32 v56, 1, v56
	v_mad_u32_u24 v56, v57, s100, v56
	v_cvt_pk_bf16_f32 v46, v46, v47
	v_cvt_pk_bf16_f32 v47, v48, v49
	ds_write_b64 v56, v[46:47]
	s_and_saveexec_b64 s[0:1], vcc
	s_xor_b64 s[0:1], exec, s[0:1]
	v_add_u32_e32 v46, v73, v113
	v_ashrrev_i32_e32 v47, 31, v46
	v_lshlrev_b64 v[46:47], 18, v[46:47]
	v_lshl_add_u64 v[46:47], v[46:47], 0, v[138:139]
	s_andn2_saveexec_b64 s[0:1], s[0:1]
	v_add_u32_e32 v46, v74, v113
	v_ashrrev_i32_e32 v47, 31, v46
	v_lshlrev_b64 v[46:47], 19, v[46:47]
	v_lshl_or_b32 v46, v153, 13, v46
	v_or_b32_e32 v46, v46, v72
	s_or_b64 exec, exec, s[0:1]
	v_pk_mul_f32 v[48:49], v[52:53], v[68:69]
	v_pk_mul_f32 v[50:51], v[50:51], v[66:67]
	v_lshrrev_b32_e32 v47, s98, v46
	v_and_b32_e32 v46, 0xff, v46
	v_and_b32_e32 v47, 0xff, v47
	v_lshlrev_b32_e32 v46, 1, v46
	v_mad_u32_u24 v46, v47, s100, v46
	v_cvt_pk_bf16_f32 v50, v50, v51
	v_cvt_pk_bf16_f32 v51, v48, v49
	ds_write_b64 v46, v[50:51]
	s_and_saveexec_b64 s[0:1], vcc
	s_xor_b64 s[0:1], exec, s[0:1]
	v_add_u32_e32 v46, v73, v112
	v_ashrrev_i32_e32 v47, 31, v46
	v_lshlrev_b64 v[46:47], 18, v[46:47]
	v_mov_b32_e32 v63, v139
	v_lshl_add_u64 v[46:47], v[46:47], 0, v[62:63]
	s_andn2_saveexec_b64 s[0:1], s[0:1]
	v_add_u32_e32 v46, v74, v112
	v_ashrrev_i32_e32 v47, 31, v46
	v_lshlrev_b64 v[46:47], 19, v[46:47]
	v_lshl_or_b32 v46, v145, 13, v46
	v_or_b32_e32 v46, v46, v72
	s_or_b64 exec, exec, s[0:1]
	v_pk_mul_f32 v[44:45], v[44:45], v[68:69]
	v_pk_mul_f32 v[42:43], v[42:43], v[66:67]
	v_lshrrev_b32_e32 v47, s98, v46
	v_and_b32_e32 v46, 0xff, v46
	v_and_b32_e32 v47, 0xff, v47
	v_lshlrev_b32_e32 v46, 1, v46
	v_mad_u32_u24 v46, v47, s100, v46
	v_cvt_pk_bf16_f32 v42, v42, v43
	v_cvt_pk_bf16_f32 v43, v44, v45
	ds_write_b64 v46, v[42:43]
	s_and_saveexec_b64 s[0:1], vcc
	s_xor_b64 s[0:1], exec, s[0:1]
	v_add_u32_e32 v42, v73, v108
	v_ashrrev_i32_e32 v43, 31, v42
	v_lshlrev_b64 v[42:43], 18, v[42:43]
	v_mov_b32_e32 v59, v139
	v_lshl_add_u64 v[42:43], v[42:43], 0, v[58:59]
	s_andn2_saveexec_b64 s[0:1], s[0:1]
	v_add_u32_e32 v42, v74, v108
	v_ashrrev_i32_e32 v43, 31, v42
	v_lshlrev_b64 v[42:43], 19, v[42:43]
	v_lshl_or_b32 v42, v146, 13, v42
	v_or_b32_e32 v42, v42, v72
	s_or_b64 exec, exec, s[0:1]
	v_pk_mul_f32 v[40:41], v[40:41], v[68:69]
	v_pk_mul_f32 v[38:39], v[38:39], v[66:67]
	v_lshrrev_b32_e32 v43, s98, v42
	v_and_b32_e32 v42, 0xff, v42
	v_and_b32_e32 v43, 0xff, v43
	v_lshlrev_b32_e32 v42, 1, v42
	v_mad_u32_u24 v42, v43, s100, v42
	v_cvt_pk_bf16_f32 v38, v38, v39
	v_cvt_pk_bf16_f32 v39, v40, v41
	ds_write_b64 v42, v[38:39]
	s_and_saveexec_b64 s[0:1], vcc
	s_xor_b64 s[0:1], exec, s[0:1]
	v_add_u32_e32 v38, v73, v106
	v_ashrrev_i32_e32 v39, 31, v38
	v_lshlrev_b64 v[38:39], 18, v[38:39]
	v_mov_b32_e32 v55, v139
	v_lshl_add_u64 v[38:39], v[38:39], 0, v[54:55]
	s_andn2_saveexec_b64 s[0:1], s[0:1]
	v_add_u32_e32 v38, v74, v106
	v_ashrrev_i32_e32 v39, 31, v38
	v_lshlrev_b64 v[38:39], 19, v[38:39]
	v_lshl_or_b32 v38, v128, 13, v38
	v_or_b32_e32 v38, v38, v72
	s_or_b64 exec, exec, s[0:1]
	v_pk_mul_f32 v[36:37], v[36:37], v[68:69]
	v_pk_mul_f32 v[34:35], v[34:35], v[66:67]
	v_add_u32_e32 v40, 0x90, v144
	v_lshrrev_b32_e32 v39, s98, v38
	v_and_b32_e32 v38, 0xff, v38
	v_and_b32_e32 v39, 0xff, v39
	v_lshlrev_b32_e32 v38, 1, v38
	v_mad_u32_u24 v38, v39, s100, v38
	v_cvt_pk_bf16_f32 v34, v34, v35
	v_cvt_pk_bf16_f32 v35, v36, v37
	v_ashrrev_i32_e32 v41, 31, v40
	ds_write_b64 v38, v[34:35]
	v_lshl_add_u64 v[34:35], v[40:41], 2, s[40:41]
	global_load_dwordx4 v[34:37], v[34:35], off
	v_add_u32_e32 v38, 0xffffc090, v144
	v_lshrrev_b32_e32 v38, 9, v38
	v_and_b32_e32 v43, 0xffc, v40
	v_cmp_lt_i32_e32 vcc, s81, v40
	v_and_b32_e32 v41, 0x7ffff8, v38
	v_or3_b32 v138, v43, v155, s82
	s_and_saveexec_b64 s[0:1], vcc
	s_xor_b64 s[0:1], exec, s[0:1]
	v_add_u32_e32 v38, v41, v154
	v_ashrrev_i32_e32 v39, 31, v38
	v_lshlrev_b64 v[38:39], 18, v[38:39]
	v_lshl_add_u64 v[38:39], v[38:39], 0, v[138:139]
	s_or_saveexec_b64 s[0:1], s[0:1]
	v_ashrrev_i32_e32 v42, 10, v40
	v_and_b32_e32 v42, -8, v42
	v_and_b32_e32 v40, 0x1ffc, v40
	s_xor_b64 exec, exec, s[0:1]
	v_add_u32_e32 v38, v42, v154
	v_ashrrev_i32_e32 v39, 31, v38
	v_lshlrev_b64 v[38:39], 19, v[38:39]
	v_lshl_or_b32 v38, v153, 13, v38
	v_or_b32_e32 v38, v38, v40
	s_or_b64 exec, exec, s[0:1]
	v_mov_b64_e32 v[44:45], s[64:65]
	s_waitcnt vmcnt(0)
	v_pk_fma_f32 v[34:35], v[34:35], s[62:63], v[44:45] op_sel_hi:[1,0,0]
	v_pk_fma_f32 v[36:37], v[36:37], s[62:63], v[44:45] op_sel_hi:[1,0,0]
	v_mul_f32_e32 v46, 0x4b800000, v34
	v_cmp_gt_f32_e64 s[0:1], s82, v34
	v_cmp_gt_f32_e64 s[8:9], s82, v35
	v_mul_f32_e32 v44, 0x4b800000, v36
	v_cndmask_b32_e64 v34, v34, v46, s[0:1]
	v_mul_f32_e32 v46, 0x4b800000, v35
	v_cmp_gt_f32_e64 s[10:11], s82, v36
	v_cndmask_b32_e64 v35, v35, v46, s[8:9]
	v_cmp_gt_f32_e64 s[14:15], s82, v37
	v_cndmask_b32_e64 v36, v36, v44, s[10:11]
	v_mul_f32_e32 v44, 0x4b800000, v37
	v_rsq_f32_e32 v34, v34
	v_rsq_f32_e32 v35, v35
	v_cndmask_b32_e64 v37, v37, v44, s[14:15]
	v_rsq_f32_e32 v36, v36
	v_rsq_f32_e32 v37, v37
	v_pk_mul_f32 v[44:45], v[34:35], s[66:67] op_sel_hi:[1,0]
	v_lshrrev_b32_e32 v39, s98, v38
	v_and_b32_e32 v38, 0xff, v38
	v_and_b32_e32 v39, 0xff, v39
	v_lshlrev_b32_e32 v38, 1, v38
	v_mad_u32_u24 v38, v39, s100, v38
	v_cndmask_b32_e64 v35, v35, v45, s[8:9]
	v_cndmask_b32_e64 v34, v34, v44, s[0:1]
	v_pk_mul_f32 v[44:45], v[36:37], s[66:67] op_sel_hi:[1,0]
	v_pk_mul_f32 v[30:31], v[30:31], v[34:35]
	v_cndmask_b32_e64 v37, v37, v45, s[14:15]
	v_cndmask_b32_e64 v36, v36, v44, s[10:11]
	v_pk_mul_f32 v[32:33], v[32:33], v[36:37]
	v_cvt_pk_bf16_f32 v30, v30, v31
	v_cvt_pk_bf16_f32 v31, v32, v33
	ds_write_b64 v38, v[30:31]
	v_or3_b32 v30, v43, v156, s82
	s_and_saveexec_b64 s[0:1], vcc
	s_xor_b64 s[0:1], exec, s[0:1]
	v_add_u32_e32 v32, v41, v147
	v_ashrrev_i32_e32 v33, 31, v32
	v_lshlrev_b64 v[32:33], 18, v[32:33]
	v_mov_b32_e32 v31, v139
	v_lshl_add_u64 v[32:33], v[32:33], 0, v[30:31]
	s_andn2_saveexec_b64 s[0:1], s[0:1]
	v_add_u32_e32 v32, v42, v147
	v_ashrrev_i32_e32 v33, 31, v32
	v_lshlrev_b64 v[32:33], 19, v[32:33]
	v_lshl_or_b32 v31, v145, 13, v32
	v_or_b32_e32 v32, v31, v40
	s_or_b64 exec, exec, s[0:1]
	v_pk_mul_f32 v[28:29], v[28:29], v[36:37]
	v_pk_mul_f32 v[26:27], v[26:27], v[34:35]
	v_lshrrev_b32_e32 v33, s98, v32
	v_and_b32_e32 v32, 0xff, v32
	v_and_b32_e32 v33, 0xff, v33
	v_lshlrev_b32_e32 v32, 1, v32
	v_mad_u32_u24 v32, v33, s100, v32
	v_cvt_pk_bf16_f32 v26, v26, v27
	v_cvt_pk_bf16_f32 v27, v28, v29
	ds_write_b64 v32, v[26:27]
	v_or3_b32 v26, v43, v157, s82
	s_and_saveexec_b64 s[0:1], vcc
	s_xor_b64 s[0:1], exec, s[0:1]
	v_add_u32_e32 v28, v41, v129
	v_ashrrev_i32_e32 v29, 31, v28
	v_lshlrev_b64 v[28:29], 18, v[28:29]
	v_mov_b32_e32 v27, v139
	v_lshl_add_u64 v[28:29], v[28:29], 0, v[26:27]
	s_andn2_saveexec_b64 s[0:1], s[0:1]
	v_add_u32_e32 v28, v42, v129
	v_ashrrev_i32_e32 v29, 31, v28
	v_lshlrev_b64 v[28:29], 19, v[28:29]
	v_lshl_or_b32 v27, v146, 13, v28
	v_or_b32_e32 v28, v27, v40
	s_or_b64 exec, exec, s[0:1]
	v_pk_mul_f32 v[24:25], v[24:25], v[36:37]
	v_pk_mul_f32 v[22:23], v[22:23], v[34:35]
	v_lshrrev_b32_e32 v29, s98, v28
	v_and_b32_e32 v28, 0xff, v28
	v_and_b32_e32 v29, 0xff, v29
	v_lshlrev_b32_e32 v28, 1, v28
	v_mad_u32_u24 v28, v29, s100, v28
	v_cvt_pk_bf16_f32 v22, v22, v23
	v_cvt_pk_bf16_f32 v23, v24, v25
	ds_write_b64 v28, v[22:23]
	v_or3_b32 v22, v43, v125, s82
	s_and_saveexec_b64 s[0:1], vcc
	s_xor_b64 s[0:1], exec, s[0:1]
	v_add_u32_e32 v24, v41, v124
	v_ashrrev_i32_e32 v25, 31, v24
	v_lshlrev_b64 v[24:25], 18, v[24:25]
	v_mov_b32_e32 v23, v139
	v_lshl_add_u64 v[24:25], v[24:25], 0, v[22:23]
	s_andn2_saveexec_b64 s[0:1], s[0:1]
	v_add_u32_e32 v24, v42, v124
	v_ashrrev_i32_e32 v25, 31, v24
	v_lshlrev_b64 v[24:25], 19, v[24:25]
	v_lshl_or_b32 v23, v128, 13, v24
	v_or_b32_e32 v24, v23, v40
	s_or_b64 exec, exec, s[0:1]
	v_pk_mul_f32 v[16:17], v[16:17], v[36:37]
	v_pk_mul_f32 v[14:15], v[14:15], v[34:35]
	v_lshrrev_b32_e32 v25, s98, v24
	v_and_b32_e32 v24, 0xff, v24
	v_and_b32_e32 v25, 0xff, v25
	v_lshlrev_b32_e32 v24, 1, v24
	v_mad_u32_u24 v24, v25, s100, v24
	v_cvt_pk_bf16_f32 v14, v14, v15
	v_cvt_pk_bf16_f32 v15, v16, v17
	ds_write_b64 v24, v[14:15]
	s_and_saveexec_b64 s[0:1], vcc
	s_xor_b64 s[0:1], exec, s[0:1]
	v_add_u32_e32 v14, v41, v113
	v_ashrrev_i32_e32 v15, 31, v14
	v_lshlrev_b64 v[14:15], 18, v[14:15]
	v_lshl_add_u64 v[14:15], v[14:15], 0, v[138:139]
	s_andn2_saveexec_b64 s[0:1], s[0:1]
	v_add_u32_e32 v14, v42, v113
	v_ashrrev_i32_e32 v15, 31, v14
	v_lshlrev_b64 v[14:15], 19, v[14:15]
	v_lshl_or_b32 v14, v153, 13, v14
	v_or_b32_e32 v14, v14, v40
	s_or_b64 exec, exec, s[0:1]
	v_pk_mul_f32 v[16:17], v[20:21], v[36:37]
	v_pk_mul_f32 v[18:19], v[18:19], v[34:35]
	v_lshrrev_b32_e32 v15, s98, v14
	v_and_b32_e32 v14, 0xff, v14
	v_and_b32_e32 v15, 0xff, v15
	v_lshlrev_b32_e32 v14, 1, v14
	v_mad_u32_u24 v14, v15, s100, v14
	v_cvt_pk_bf16_f32 v18, v18, v19
	v_cvt_pk_bf16_f32 v19, v16, v17
	ds_write_b64 v14, v[18:19]
	s_and_saveexec_b64 s[0:1], vcc
	s_xor_b64 s[0:1], exec, s[0:1]
	v_add_u32_e32 v14, v41, v112
	v_ashrrev_i32_e32 v15, 31, v14
	v_lshlrev_b64 v[14:15], 18, v[14:15]
	v_mov_b32_e32 v31, v139
	v_lshl_add_u64 v[14:15], v[14:15], 0, v[30:31]
	s_andn2_saveexec_b64 s[0:1], s[0:1]
	v_add_u32_e32 v14, v42, v112
	v_ashrrev_i32_e32 v15, 31, v14
	v_lshlrev_b64 v[14:15], 19, v[14:15]
	v_lshl_or_b32 v14, v145, 13, v14
	v_or_b32_e32 v14, v14, v40
	s_or_b64 exec, exec, s[0:1]
	v_pk_mul_f32 v[12:13], v[12:13], v[36:37]
	v_pk_mul_f32 v[10:11], v[10:11], v[34:35]
	v_lshrrev_b32_e32 v15, s98, v14
	v_and_b32_e32 v14, 0xff, v14
	v_and_b32_e32 v15, 0xff, v15
	v_lshlrev_b32_e32 v14, 1, v14
	v_mad_u32_u24 v14, v15, s100, v14
	v_cvt_pk_bf16_f32 v10, v10, v11
	v_cvt_pk_bf16_f32 v11, v12, v13
	ds_write_b64 v14, v[10:11]
	s_and_saveexec_b64 s[0:1], vcc
	s_xor_b64 s[0:1], exec, s[0:1]
	v_add_u32_e32 v10, v41, v108
	v_ashrrev_i32_e32 v11, 31, v10
	v_lshlrev_b64 v[10:11], 18, v[10:11]
	v_mov_b32_e32 v27, v139
	v_lshl_add_u64 v[10:11], v[10:11], 0, v[26:27]
	s_andn2_saveexec_b64 s[0:1], s[0:1]
	v_add_u32_e32 v10, v42, v108
	v_ashrrev_i32_e32 v11, 31, v10
	v_lshlrev_b64 v[10:11], 19, v[10:11]
	v_lshl_or_b32 v10, v146, 13, v10
	v_or_b32_e32 v10, v10, v40
	s_or_b64 exec, exec, s[0:1]
	v_pk_mul_f32 v[8:9], v[8:9], v[36:37]
	v_pk_mul_f32 v[6:7], v[6:7], v[34:35]
	v_lshrrev_b32_e32 v11, s98, v10
	v_and_b32_e32 v10, 0xff, v10
	v_and_b32_e32 v11, 0xff, v11
	v_lshlrev_b32_e32 v10, 1, v10
	v_mad_u32_u24 v10, v11, s100, v10
	v_cvt_pk_bf16_f32 v6, v6, v7
	v_cvt_pk_bf16_f32 v7, v8, v9
	ds_write_b64 v10, v[6:7]
	s_and_saveexec_b64 s[0:1], vcc
	s_xor_b64 s[0:1], exec, s[0:1]
	v_add_u32_e32 v6, v41, v106
	v_ashrrev_i32_e32 v7, 31, v6
	v_lshlrev_b64 v[6:7], 18, v[6:7]
	v_mov_b32_e32 v23, v139
	v_lshl_add_u64 v[6:7], v[6:7], 0, v[22:23]
	s_andn2_saveexec_b64 s[0:1], s[0:1]
	v_add_u32_e32 v6, v42, v106
	v_ashrrev_i32_e32 v7, 31, v6
	v_lshlrev_b64 v[6:7], 19, v[6:7]
	v_lshl_or_b32 v6, v128, 13, v6
	v_or_b32_e32 v6, v6, v40
	s_or_b64 exec, exec, s[0:1]
	v_pk_mul_f32 v[4:5], v[4:5], v[36:37]
	v_pk_mul_f32 v[2:3], v[2:3], v[34:35]
	v_lshrrev_b32_e32 v7, s98, v6
	v_and_b32_e32 v6, 0xff, v6
	v_and_b32_e32 v7, 0xff, v7
	v_lshlrev_b32_e32 v6, 1, v6
	v_mad_u32_u24 v6, v7, s100, v6
	v_cvt_pk_bf16_f32 v2, v2, v3
	v_cvt_pk_bf16_f32 v3, v4, v5
	s_and_b64 vcc, exec, s[6:7]
	s_mov_b64 s[0:1], -1
	ds_write_b64 v6, v[2:3]
	s_waitcnt lgkmcnt(0)
	s_barrier
	v_lshrrev_b32_e32 v2, 5, v0
	v_and_b32_e32 v3, 31, v0
	v_mul_u32_u24_e32 v4, 0x210, v2
	v_lshl_add_u32 v4, v3, 4, v4
	v_add_u32_e32 v5, 0x10800, v4
	s_add_i32 s99, s98, 1
	v_lshlrev_b32_e32 v6, s99, v2
	v_lshl_add_u32 v6, v3, 4, v6
	s_lshl_b32 s100, s101, 1
	v_add_u32_e32 v6, s100, v6
	v_mov_b32_e32 v7, 0
	v_lshl_add_u64 v[6:7], v[6:7], 0, s[46:47]
	s_add_i32 s99, s98, 5
	s_lshl_b32 s100, 1, s99
	s_mov_b32 s101, 0
	ds_read_b128 v[8:11], v4
	ds_read_b128 v[12:15], v4 offset:8448
	ds_read_b128 v[16:19], v4 offset:16896
	ds_read_b128 v[20:23], v4 offset:25344
	ds_read_b128 v[24:27], v4 offset:33792
	ds_read_b128 v[28:31], v4 offset:42240
	ds_read_b128 v[32:35], v4 offset:50688
	ds_read_b128 v[36:39], v4 offset:59136
	ds_read_b128 v[40:43], v5
	ds_read_b128 v[44:47], v5 offset:8448
	ds_read_b128 v[48:51], v5 offset:16896
	ds_read_b128 v[52:55], v5 offset:25344
	ds_read_b128 v[56:59], v5 offset:33792
	ds_read_b128 v[60:63], v5 offset:42240
	ds_read_b128 v[64:67], v5 offset:50688
	ds_read_b128 v[68:71], v5 offset:59136
	s_waitcnt lgkmcnt(15)
	global_store_dwordx4 v[6:7], v[8:11], off
	v_lshl_add_u64 v[6:7], v[6:7], 0, s[100:101]
	s_waitcnt lgkmcnt(14)
	global_store_dwordx4 v[6:7], v[12:15], off
	v_lshl_add_u64 v[6:7], v[6:7], 0, s[100:101]
	s_waitcnt lgkmcnt(13)
	global_store_dwordx4 v[6:7], v[16:19], off
	v_lshl_add_u64 v[6:7], v[6:7], 0, s[100:101]
	s_waitcnt lgkmcnt(12)
	global_store_dwordx4 v[6:7], v[20:23], off
	v_lshl_add_u64 v[6:7], v[6:7], 0, s[100:101]
	s_waitcnt lgkmcnt(11)
	global_store_dwordx4 v[6:7], v[24:27], off
	v_lshl_add_u64 v[6:7], v[6:7], 0, s[100:101]
	s_waitcnt lgkmcnt(10)
	global_store_dwordx4 v[6:7], v[28:31], off
	v_lshl_add_u64 v[6:7], v[6:7], 0, s[100:101]
	s_waitcnt lgkmcnt(9)
	global_store_dwordx4 v[6:7], v[32:35], off
	v_lshl_add_u64 v[6:7], v[6:7], 0, s[100:101]
	s_waitcnt lgkmcnt(8)
	global_store_dwordx4 v[6:7], v[36:39], off
	v_lshl_add_u64 v[6:7], v[6:7], 0, s[100:101]
	s_waitcnt lgkmcnt(7)
	global_store_dwordx4 v[6:7], v[40:43], off
	v_lshl_add_u64 v[6:7], v[6:7], 0, s[100:101]
	s_waitcnt lgkmcnt(6)
	global_store_dwordx4 v[6:7], v[44:47], off
	v_lshl_add_u64 v[6:7], v[6:7], 0, s[100:101]
	s_waitcnt lgkmcnt(5)
	global_store_dwordx4 v[6:7], v[48:51], off
	v_lshl_add_u64 v[6:7], v[6:7], 0, s[100:101]
	s_waitcnt lgkmcnt(4)
	global_store_dwordx4 v[6:7], v[52:55], off
	v_lshl_add_u64 v[6:7], v[6:7], 0, s[100:101]
	s_waitcnt lgkmcnt(3)
	global_store_dwordx4 v[6:7], v[56:59], off
	v_lshl_add_u64 v[6:7], v[6:7], 0, s[100:101]
	s_waitcnt lgkmcnt(2)
	global_store_dwordx4 v[6:7], v[60:63], off
	v_lshl_add_u64 v[6:7], v[6:7], 0, s[100:101]
	s_waitcnt lgkmcnt(1)
	global_store_dwordx4 v[6:7], v[64:67], off
	v_lshl_add_u64 v[6:7], v[6:7], 0, s[100:101]
	s_waitcnt lgkmcnt(0)
	global_store_dwordx4 v[6:7], v[68:71], off
	v_lshl_add_u64 v[6:7], v[6:7], 0, s[100:101]
	s_cbranch_vccnz .LBB0_614
	s_andn2_b64 vcc, exec, s[50:51]
	s_cbranch_vccnz .LBB0_613
	s_barrier
	s_branch .LBB0_613
